# batched Q block staging, FFN-in first K-iteration peeled with zero C operand (no accumulator zero-fill), p-to-bf16 conversion loop with 8 loads in flight
# speedup vs baseline: 1.0302x; 1.0082x over previous
.LBB0_66:
	s_ashr_i32 s73, s72, 31
	s_lshl_b64 s[0:1], s[72:73], 9
	v_lshl_add_u64 v[2:3], s[0:1], 0, v[14:15]
	s_mov_b64 s[0:1], 0x400000
	v_cmp_gt_u64_e32 vcc, s[0:1], v[2:3]
	s_and_saveexec_b64 s[0:1], vcc
	s_cbranch_execz .LBB0_69
	s_ashr_i32 s9, s70, 31
	s_mov_b32 s8, s70
	s_lshl_b64 s[4:5], s[8:9], 9
	s_lshl_b64 s[6:7], s[72:73], 12
	s_add_u32 s6, s46, s6
	s_addc_u32 s7, s47, s7
	v_lshl_add_u64 v[4:5], v[14:15], 3, s[6:7]
	s_mov_b64 s[6:7], 0x18200000
	v_lshl_add_u64 v[4:5], v[4:5], 0, s[6:7]
	s_lshl_b64 s[6:7], s[8:9], 12
	s_lshl_b64 s[10:11], s[72:73], 13
	s_add_u32 s10, s18, s10
	s_addc_u32 s11, s19, s11
	v_lshl_add_u64 v[6:7], v[14:15], 4, s[10:11]
	s_lshl_b64 s[8:9], s[8:9], 13
	s_mov_b64 s[12:13], 0x3fffff
	s_lshl_b64 s[100:101], s[4:5], 3
	s_sub_u32 s100, s100, s4
	s_subb_u32 s101, s101, s5
	s_mov_b64 s[10:11], exec
.Lp8_loop:
	v_lshl_add_u64 v[200:201], v[2:3], 0, s[100:101]
	v_cmp_ge_u64_e32 vcc, s[12:13], v[200:201]
	s_nop 1
	s_and_b64 exec, s[10:11], vcc
	s_cbranch_execz .Lp8_done
	global_load_dwordx4 v[204:207], v[6:7], off
	v_lshl_add_u64 v[6:7], v[6:7], 0, s[8:9]
	global_load_dwordx4 v[208:211], v[6:7], off
	v_lshl_add_u64 v[6:7], v[6:7], 0, s[8:9]
	global_load_dwordx4 v[212:215], v[6:7], off
	v_lshl_add_u64 v[6:7], v[6:7], 0, s[8:9]
	global_load_dwordx4 v[216:219], v[6:7], off
	v_lshl_add_u64 v[6:7], v[6:7], 0, s[8:9]
	global_load_dwordx4 v[220:223], v[6:7], off
	v_lshl_add_u64 v[6:7], v[6:7], 0, s[8:9]
	global_load_dwordx4 v[224:227], v[6:7], off
	v_lshl_add_u64 v[6:7], v[6:7], 0, s[8:9]
	global_load_dwordx4 v[228:231], v[6:7], off
	v_lshl_add_u64 v[6:7], v[6:7], 0, s[8:9]
	global_load_dwordx4 v[232:235], v[6:7], off
	v_lshl_add_u64 v[6:7], v[6:7], 0, s[8:9]
	v_lshl_add_u64 v[2:3], v[200:201], 0, s[4:5]
	s_waitcnt vmcnt(7)
	v_cvt_pk_bf16_f32 v204, v204, v205
	v_cvt_pk_bf16_f32 v205, v206, v207
	global_store_dwordx2 v[4:5], v[204:205], off
	v_lshl_add_u64 v[4:5], v[4:5], 0, s[6:7]
	s_waitcnt vmcnt(7)
	v_cvt_pk_bf16_f32 v208, v208, v209
	v_cvt_pk_bf16_f32 v209, v210, v211
	global_store_dwordx2 v[4:5], v[208:209], off
	v_lshl_add_u64 v[4:5], v[4:5], 0, s[6:7]
	s_waitcnt vmcnt(7)
	v_cvt_pk_bf16_f32 v212, v212, v213
	v_cvt_pk_bf16_f32 v213, v214, v215
	global_store_dwordx2 v[4:5], v[212:213], off
	v_lshl_add_u64 v[4:5], v[4:5], 0, s[6:7]
	s_waitcnt vmcnt(7)
	v_cvt_pk_bf16_f32 v216, v216, v217
	v_cvt_pk_bf16_f32 v217, v218, v219
	global_store_dwordx2 v[4:5], v[216:217], off
	v_lshl_add_u64 v[4:5], v[4:5], 0, s[6:7]
	s_waitcnt vmcnt(7)
	v_cvt_pk_bf16_f32 v220, v220, v221
	v_cvt_pk_bf16_f32 v221, v222, v223
	global_store_dwordx2 v[4:5], v[220:221], off
	v_lshl_add_u64 v[4:5], v[4:5], 0, s[6:7]
	s_waitcnt vmcnt(7)
	v_cvt_pk_bf16_f32 v224, v224, v225
	v_cvt_pk_bf16_f32 v225, v226, v227
	global_store_dwordx2 v[4:5], v[224:225], off
	v_lshl_add_u64 v[4:5], v[4:5], 0, s[6:7]
	s_waitcnt vmcnt(7)
	v_cvt_pk_bf16_f32 v228, v228, v229
	v_cvt_pk_bf16_f32 v229, v230, v231
	global_store_dwordx2 v[4:5], v[228:229], off
	v_lshl_add_u64 v[4:5], v[4:5], 0, s[6:7]
	s_waitcnt vmcnt(7)
	v_cvt_pk_bf16_f32 v232, v232, v233
	v_cvt_pk_bf16_f32 v233, v234, v235
	global_store_dwordx2 v[4:5], v[232:233], off
	v_lshl_add_u64 v[4:5], v[4:5], 0, s[6:7]
	s_branch .Lp8_loop
.Lp8_done:
	s_mov_b64 exec, s[10:11]
	v_cmp_ge_u64_e32 vcc, s[12:13], v[2:3]
	s_nop 1
	s_and_b64 exec, exec, vcc
	s_mov_b64 s[10:11], 0
	s_cbranch_execz .LBB0_69

.LBB0_125:
	s_ashr_i32 s9, s8, 31
	s_lshl_b64 s[22:23], s[8:9], 19
	s_add_u32 s40, s42, s22
	s_addc_u32 s41, s43, s23
	s_and_b64 s[22:23], s[38:39], exec
	s_cselect_b32 s9, s41, s11
	s_cselect_b32 s22, s40, s10
	s_ashr_i32 s7, s6, 31
	s_lshl_b64 s[24:25], s[6:7], 19
	s_add_u32 s82, s19, s24
	s_addc_u32 s83, s50, s25
	s_and_b64 s[24:25], s[38:39], exec
	s_cselect_b32 s7, s83, s37
	s_cselect_b32 s23, s82, s36
	s_add_u32 s10, s10, 0x40080
	s_addc_u32 s11, s11, 0
	s_add_u32 s24, s36, 0x100
	s_addc_u32 s25, s37, 0
	s_mov_b32 s26, -2
	s_add_u32 s13, s10, 0xfffc0080
	s_addc_u32 s27, s11, -1
	s_add_i32 s28, 0, 0x10000
	s_cmp_eq_u32 s26, 12
	s_cselect_b32 s49, s9, s27
	s_cselect_b32 s48, s22, s13
	v_add_u32_e32 v0, s28, v150
	s_cselect_b32 s37, s7, s25
	s_cselect_b32 s36, s23, s24
	s_add_i32 s13, 0, 0x14000
	ds_read_b128 v[166:169], v0
	ds_read_b128 v[170:173], v0 offset:1024
	ds_read_b128 v[174:177], v0 offset:2048
	ds_read_b128 v[178:181], v0 offset:3072
	v_add_u32_e32 v0, s13, v150
	ds_read_b128 v[182:185], v0
	ds_read_b128 v[186:189], v0 offset:1024
	ds_read_b128 v[190:193], v0 offset:2048
	ds_read_b128 v[194:197], v0 offset:3072
	v_lshl_add_u64 v[130:131], s[10:11], 0, v[146:147]
	s_add_i32 m0, s52, 0xc000
	ds_read_b128 v[198:201], v152
	ds_read_b128 v[202:205], v152 offset:1024
	ds_read_b128 v[206:209], v152 offset:2048
	ds_read_b128 v[210:213], v152 offset:3072
	ds_read_b128 v[214:217], v152 offset:4096
	ds_read_b128 v[218:221], v152 offset:5120
	ds_read_b128 v[222:225], v152 offset:6144
	ds_read_b128 v[226:229], v152 offset:7168
	global_load_lds_dwordx4 v[130:131], off
	v_lshl_add_u64 v[130:131], s[10:11], 0, v[148:149]
	s_add_i32 m0, s52, 0xe000
	s_nop 0
	global_load_lds_dwordx4 v[130:131], off
	s_waitcnt vmcnt(8)
	s_waitcnt lgkmcnt(0)
	s_barrier
	s_setprio 1
	s_waitcnt lgkmcnt(0)
	v_mfma_f32_16x16x32_bf16 v[126:129], v[166:169], v[198:201], 0
	v_mfma_f32_16x16x32_bf16 v[114:117], v[174:177], v[198:201], 0
	v_mfma_f32_16x16x32_bf16 v[110:113], v[166:169], v[206:209], 0
	v_mfma_f32_16x16x32_bf16 v[98:101], v[174:177], v[206:209], 0
	v_mfma_f32_16x16x32_bf16 v[94:97], v[166:169], v[214:217], 0
	v_mfma_f32_16x16x32_bf16 v[82:85], v[174:177], v[214:217], 0
	v_mfma_f32_16x16x32_bf16 v[78:81], v[166:169], v[222:225], 0
	v_mfma_f32_16x16x32_bf16 v[66:69], v[174:177], v[222:225], 0
	v_mfma_f32_16x16x32_bf16 v[126:129], v[170:173], v[202:205], v[126:129]
	v_mfma_f32_16x16x32_bf16 v[114:117], v[178:181], v[202:205], v[114:117]
	v_mfma_f32_16x16x32_bf16 v[110:113], v[170:173], v[210:213], v[110:113]
	v_mfma_f32_16x16x32_bf16 v[98:101], v[178:181], v[210:213], v[98:101]
	v_mfma_f32_16x16x32_bf16 v[94:97], v[170:173], v[218:221], v[94:97]
	v_mfma_f32_16x16x32_bf16 v[82:85], v[178:181], v[218:221], v[82:85]
	v_mfma_f32_16x16x32_bf16 v[78:81], v[170:173], v[226:229], v[78:81]
	v_mfma_f32_16x16x32_bf16 v[66:69], v[178:181], v[226:229], v[66:69]
	s_setprio 0
	s_setprio 1
	v_mfma_f32_16x16x32_bf16 v[122:125], v[182:185], v[198:201], 0
	v_mfma_f32_16x16x32_bf16 v[118:121], v[190:193], v[198:201], 0
	v_mfma_f32_16x16x32_bf16 v[106:109], v[182:185], v[206:209], 0
	v_mfma_f32_16x16x32_bf16 v[102:105], v[190:193], v[206:209], 0
	v_mfma_f32_16x16x32_bf16 v[90:93], v[182:185], v[214:217], 0
	v_mfma_f32_16x16x32_bf16 v[86:89], v[190:193], v[214:217], 0
	v_mfma_f32_16x16x32_bf16 v[74:77], v[182:185], v[222:225], 0
	v_mfma_f32_16x16x32_bf16 v[70:73], v[190:193], v[222:225], 0
	v_mfma_f32_16x16x32_bf16 v[122:125], v[186:189], v[202:205], v[122:125]
	v_mfma_f32_16x16x32_bf16 v[118:121], v[194:197], v[202:205], v[118:121]
	v_mfma_f32_16x16x32_bf16 v[106:109], v[186:189], v[210:213], v[106:109]
	v_mfma_f32_16x16x32_bf16 v[102:105], v[194:197], v[210:213], v[102:105]
	v_mfma_f32_16x16x32_bf16 v[90:93], v[186:189], v[218:221], v[90:93]
	v_mfma_f32_16x16x32_bf16 v[86:89], v[194:197], v[218:221], v[86:89]
	v_mfma_f32_16x16x32_bf16 v[74:77], v[186:189], v[226:229], v[74:77]
	v_mfma_f32_16x16x32_bf16 v[70:73], v[194:197], v[226:229], v[70:73]
	s_setprio 0
	s_barrier
	s_add_i32 s27, s28, s51
	v_lshl_add_u64 v[130:131], s[36:37], 0, v[142:143]
	s_mov_b32 m0, s27
	ds_read_b128 v[198:201], v152 offset:16384
	ds_read_b128 v[202:205], v152 offset:17408
	ds_read_b128 v[206:209], v152 offset:18432
	ds_read_b128 v[210:213], v152 offset:19456
	ds_read_b128 v[214:217], v152 offset:20480
	ds_read_b128 v[218:221], v152 offset:21504
	ds_read_b128 v[222:225], v152 offset:22528
	ds_read_b128 v[226:229], v152 offset:23552
	global_load_lds_dwordx4 v[130:131], off
	s_add_i32 m0, s27, 0x2000
	s_add_u32 s28, s36, 0x40000
	v_lshl_add_u64 v[136:137], s[36:37], 0, v[138:139]
	s_addc_u32 s29, s37, 0
	s_add_i32 s13, s13, s51
	global_load_lds_dwordx4 v[136:137], off
	v_lshl_add_u64 v[230:231], s[28:29], 0, v[142:143]
	s_mov_b32 m0, s13
	v_lshl_add_u64 v[232:233], s[48:49], 0, v[140:141]
	global_load_lds_dwordx4 v[230:231], off
	v_lshl_add_u64 v[230:231], s[28:29], 0, v[138:139]
	s_add_i32 m0, s13, 0x2000
	s_nop 0
	global_load_lds_dwordx4 v[230:231], off
	v_lshl_add_u64 v[230:231], s[48:49], 0, v[144:145]
	s_mov_b32 m0, s52
	s_nop 0
	global_load_lds_dwordx4 v[230:231], off
	s_mov_b32 m0, s53
	s_nop 0
	global_load_lds_dwordx4 v[232:233], off
	s_waitcnt vmcnt(8)
	s_waitcnt lgkmcnt(0)
	s_barrier
	s_setprio 1
	s_waitcnt lgkmcnt(0)
	v_mfma_f32_16x16x32_bf16 v[62:65], v[166:169], v[198:201], 0
	v_mfma_f32_16x16x32_bf16 v[50:53], v[174:177], v[198:201], 0
	v_mfma_f32_16x16x32_bf16 v[46:49], v[166:169], v[206:209], 0
	v_mfma_f32_16x16x32_bf16 v[34:37], v[174:177], v[206:209], 0
	v_mfma_f32_16x16x32_bf16 v[30:33], v[166:169], v[214:217], 0
	v_mfma_f32_16x16x32_bf16 v[18:21], v[174:177], v[214:217], 0
	v_mfma_f32_16x16x32_bf16 v[14:17], v[166:169], v[222:225], 0
	v_mfma_f32_16x16x32_bf16 v[6:9], v[174:177], v[222:225], 0
	v_mfma_f32_16x16x32_bf16 v[62:65], v[170:173], v[202:205], v[62:65]
	v_mfma_f32_16x16x32_bf16 v[50:53], v[178:181], v[202:205], v[50:53]
	v_mfma_f32_16x16x32_bf16 v[46:49], v[170:173], v[210:213], v[46:49]
	v_mfma_f32_16x16x32_bf16 v[34:37], v[178:181], v[210:213], v[34:37]
	v_mfma_f32_16x16x32_bf16 v[30:33], v[170:173], v[218:221], v[30:33]
	v_mfma_f32_16x16x32_bf16 v[18:21], v[178:181], v[218:221], v[18:21]
	v_mfma_f32_16x16x32_bf16 v[14:17], v[170:173], v[226:229], v[14:17]
	v_mfma_f32_16x16x32_bf16 v[6:9], v[178:181], v[226:229], v[6:9]
	s_setprio 0
	s_setprio 1
	v_mfma_f32_16x16x32_bf16 v[58:61], v[182:185], v[198:201], 0
	v_mfma_f32_16x16x32_bf16 v[54:57], v[190:193], v[198:201], 0
	v_mfma_f32_16x16x32_bf16 v[42:45], v[182:185], v[206:209], 0
	v_mfma_f32_16x16x32_bf16 v[38:41], v[190:193], v[206:209], 0
	v_mfma_f32_16x16x32_bf16 v[26:29], v[182:185], v[214:217], 0
	v_mfma_f32_16x16x32_bf16 v[22:25], v[190:193], v[214:217], 0
	v_mfma_f32_16x16x32_bf16 v[10:13], v[182:185], v[222:225], 0
	v_mfma_f32_16x16x32_bf16 v[2:5], v[190:193], v[222:225], 0
	v_mfma_f32_16x16x32_bf16 v[58:61], v[186:189], v[202:205], v[58:61]
	v_mfma_f32_16x16x32_bf16 v[54:57], v[194:197], v[202:205], v[54:57]
	v_mfma_f32_16x16x32_bf16 v[42:45], v[186:189], v[210:213], v[42:45]
	v_mfma_f32_16x16x32_bf16 v[38:41], v[194:197], v[210:213], v[38:41]
	v_mfma_f32_16x16x32_bf16 v[26:29], v[186:189], v[218:221], v[26:29]
	v_mfma_f32_16x16x32_bf16 v[22:25], v[194:197], v[218:221], v[22:25]
	v_mfma_f32_16x16x32_bf16 v[10:13], v[186:189], v[226:229], v[10:13]
	v_mfma_f32_16x16x32_bf16 v[2:5], v[194:197], v[226:229], v[2:5]
	s_setprio 0
	s_barrier
	s_add_i32 s13, 0, 0x18000
	v_add_u32_e32 v0, s13, v150
	s_add_i32 s27, 0, 0x1c000
	ds_read_b128 v[166:169], v0
	ds_read_b128 v[170:173], v0 offset:1024
	ds_read_b128 v[174:177], v0 offset:2048
	ds_read_b128 v[178:181], v0 offset:3072
	v_add_u32_e32 v0, s27, v150
	ds_read_b128 v[182:185], v0
	ds_read_b128 v[186:189], v0 offset:1024
	ds_read_b128 v[190:193], v0 offset:2048
	ds_read_b128 v[194:197], v0 offset:3072
	s_add_u32 s28, s48, 0x40000
	s_addc_u32 s29, s49, 0
	s_mov_b32 m0, s54
	v_lshl_add_u64 v[234:235], s[28:29], 0, v[144:145]
	ds_read_b128 v[198:201], v152 offset:32768
	ds_read_b128 v[202:205], v152 offset:33792
	ds_read_b128 v[206:209], v152 offset:34816
	ds_read_b128 v[210:213], v152 offset:35840
	ds_read_b128 v[214:217], v152 offset:36864
	ds_read_b128 v[218:221], v152 offset:37888
	ds_read_b128 v[222:225], v152 offset:38912
	ds_read_b128 v[226:229], v152 offset:39936
	global_load_lds_dwordx4 v[234:235], off
	v_lshl_add_u64 v[234:235], s[28:29], 0, v[140:141]
	s_mov_b32 m0, s55
	s_nop 0
	global_load_lds_dwordx4 v[234:235], off
	s_waitcnt vmcnt(8)
	s_waitcnt lgkmcnt(0)
	s_barrier
	s_setprio 1
	s_waitcnt lgkmcnt(0)
	v_mfma_f32_16x16x32_bf16 v[126:129], v[166:169], v[198:201], v[126:129]
	v_mfma_f32_16x16x32_bf16 v[114:117], v[174:177], v[198:201], v[114:117]
	v_mfma_f32_16x16x32_bf16 v[110:113], v[166:169], v[206:209], v[110:113]
	v_mfma_f32_16x16x32_bf16 v[98:101], v[174:177], v[206:209], v[98:101]
	v_mfma_f32_16x16x32_bf16 v[94:97], v[166:169], v[214:217], v[94:97]
	v_mfma_f32_16x16x32_bf16 v[82:85], v[174:177], v[214:217], v[82:85]
	v_mfma_f32_16x16x32_bf16 v[78:81], v[166:169], v[222:225], v[78:81]
	v_mfma_f32_16x16x32_bf16 v[66:69], v[174:177], v[222:225], v[66:69]
	v_mfma_f32_16x16x32_bf16 v[126:129], v[170:173], v[202:205], v[126:129]
	v_mfma_f32_16x16x32_bf16 v[114:117], v[178:181], v[202:205], v[114:117]
	v_mfma_f32_16x16x32_bf16 v[110:113], v[170:173], v[210:213], v[110:113]
	v_mfma_f32_16x16x32_bf16 v[98:101], v[178:181], v[210:213], v[98:101]
	v_mfma_f32_16x16x32_bf16 v[94:97], v[170:173], v[218:221], v[94:97]
	v_mfma_f32_16x16x32_bf16 v[82:85], v[178:181], v[218:221], v[82:85]
	v_mfma_f32_16x16x32_bf16 v[78:81], v[170:173], v[226:229], v[78:81]
	v_mfma_f32_16x16x32_bf16 v[66:69], v[178:181], v[226:229], v[66:69]
	s_setprio 0
	s_setprio 1
	v_mfma_f32_16x16x32_bf16 v[122:125], v[182:185], v[198:201], v[122:125]
	v_mfma_f32_16x16x32_bf16 v[118:121], v[190:193], v[198:201], v[118:121]
	v_mfma_f32_16x16x32_bf16 v[106:109], v[182:185], v[206:209], v[106:109]
	v_mfma_f32_16x16x32_bf16 v[102:105], v[190:193], v[206:209], v[102:105]
	v_mfma_f32_16x16x32_bf16 v[90:93], v[182:185], v[214:217], v[90:93]
	v_mfma_f32_16x16x32_bf16 v[86:89], v[190:193], v[214:217], v[86:89]
	v_mfma_f32_16x16x32_bf16 v[74:77], v[182:185], v[222:225], v[74:77]
	v_mfma_f32_16x16x32_bf16 v[70:73], v[190:193], v[222:225], v[70:73]
	v_mfma_f32_16x16x32_bf16 v[122:125], v[186:189], v[202:205], v[122:125]
	v_mfma_f32_16x16x32_bf16 v[118:121], v[194:197], v[202:205], v[118:121]
	v_mfma_f32_16x16x32_bf16 v[106:109], v[186:189], v[210:213], v[106:109]
	v_mfma_f32_16x16x32_bf16 v[102:105], v[194:197], v[210:213], v[102:105]
	v_mfma_f32_16x16x32_bf16 v[90:93], v[186:189], v[218:221], v[90:93]
	v_mfma_f32_16x16x32_bf16 v[86:89], v[194:197], v[218:221], v[86:89]
	v_mfma_f32_16x16x32_bf16 v[74:77], v[186:189], v[226:229], v[74:77]
	v_mfma_f32_16x16x32_bf16 v[70:73], v[194:197], v[226:229], v[70:73]
	s_setprio 0
	s_barrier
	s_add_i32 s13, s13, s51
	v_lshl_add_u64 v[130:131], v[130:131], 0, s[84:85]
	s_mov_b32 m0, s13
	ds_read_b128 v[198:201], v152 offset:49152
	ds_read_b128 v[202:205], v152 offset:50176
	ds_read_b128 v[206:209], v152 offset:51200
	ds_read_b128 v[210:213], v152 offset:52224
	ds_read_b128 v[214:217], v152 offset:53248
	ds_read_b128 v[218:221], v152 offset:54272
	ds_read_b128 v[222:225], v152 offset:55296
	ds_read_b128 v[226:229], v152 offset:56320
	global_load_lds_dwordx4 v[130:131], off
	s_add_i32 m0, s13, 0x2000
	s_add_u32 s28, s36, 0x40080
	v_lshl_add_u64 v[130:131], v[136:137], 0, s[84:85]
	s_addc_u32 s29, s37, 0
	s_add_i32 s13, s27, s51
	global_load_lds_dwordx4 v[130:131], off
	v_lshl_add_u64 v[130:131], s[28:29], 0, v[142:143]
	s_mov_b32 m0, s13
	s_nop 0
	global_load_lds_dwordx4 v[130:131], off
	v_lshl_add_u64 v[130:131], s[28:29], 0, v[138:139]
	s_add_i32 m0, s13, 0x2000
	s_nop 0
	global_load_lds_dwordx4 v[130:131], off
	v_lshl_add_u64 v[130:131], v[230:231], 0, s[84:85]
	s_mov_b32 m0, s60
	s_nop 0
	global_load_lds_dwordx4 v[130:131], off
	v_lshl_add_u64 v[130:131], v[232:233], 0, s[84:85]
	s_mov_b32 m0, s61
	s_nop 0
	global_load_lds_dwordx4 v[130:131], off
	s_waitcnt vmcnt(8)
	s_waitcnt lgkmcnt(0)
	s_barrier
	s_setprio 1
	s_waitcnt lgkmcnt(0)
	v_mfma_f32_16x16x32_bf16 v[62:65], v[166:169], v[198:201], v[62:65]
	v_mfma_f32_16x16x32_bf16 v[50:53], v[174:177], v[198:201], v[50:53]
	v_mfma_f32_16x16x32_bf16 v[46:49], v[166:169], v[206:209], v[46:49]
	v_mfma_f32_16x16x32_bf16 v[34:37], v[174:177], v[206:209], v[34:37]
	v_mfma_f32_16x16x32_bf16 v[30:33], v[166:169], v[214:217], v[30:33]
	v_mfma_f32_16x16x32_bf16 v[18:21], v[174:177], v[214:217], v[18:21]
	v_mfma_f32_16x16x32_bf16 v[14:17], v[166:169], v[222:225], v[14:17]
	v_mfma_f32_16x16x32_bf16 v[6:9], v[174:177], v[222:225], v[6:9]
	v_mfma_f32_16x16x32_bf16 v[62:65], v[170:173], v[202:205], v[62:65]
	v_mfma_f32_16x16x32_bf16 v[50:53], v[178:181], v[202:205], v[50:53]
	v_mfma_f32_16x16x32_bf16 v[46:49], v[170:173], v[210:213], v[46:49]
	v_mfma_f32_16x16x32_bf16 v[34:37], v[178:181], v[210:213], v[34:37]
	v_mfma_f32_16x16x32_bf16 v[30:33], v[170:173], v[218:221], v[30:33]
	v_mfma_f32_16x16x32_bf16 v[18:21], v[178:181], v[218:221], v[18:21]
	v_mfma_f32_16x16x32_bf16 v[14:17], v[170:173], v[226:229], v[14:17]
	v_mfma_f32_16x16x32_bf16 v[6:9], v[178:181], v[226:229], v[6:9]
	s_setprio 0
	s_setprio 1
	v_mfma_f32_16x16x32_bf16 v[58:61], v[182:185], v[198:201], v[58:61]
	v_mfma_f32_16x16x32_bf16 v[54:57], v[190:193], v[198:201], v[54:57]
	v_mfma_f32_16x16x32_bf16 v[42:45], v[182:185], v[206:209], v[42:45]
	v_mfma_f32_16x16x32_bf16 v[38:41], v[190:193], v[206:209], v[38:41]
	v_mfma_f32_16x16x32_bf16 v[26:29], v[182:185], v[214:217], v[26:29]
	v_mfma_f32_16x16x32_bf16 v[22:25], v[190:193], v[214:217], v[22:25]
	v_mfma_f32_16x16x32_bf16 v[10:13], v[182:185], v[222:225], v[10:13]
	v_mfma_f32_16x16x32_bf16 v[2:5], v[190:193], v[222:225], v[2:5]
	v_mfma_f32_16x16x32_bf16 v[58:61], v[186:189], v[202:205], v[58:61]
	v_mfma_f32_16x16x32_bf16 v[54:57], v[194:197], v[202:205], v[54:57]
	v_mfma_f32_16x16x32_bf16 v[42:45], v[186:189], v[210:213], v[42:45]
	v_mfma_f32_16x16x32_bf16 v[38:41], v[194:197], v[210:213], v[38:41]
	v_mfma_f32_16x16x32_bf16 v[26:29], v[186:189], v[218:221], v[26:29]
	v_mfma_f32_16x16x32_bf16 v[22:25], v[194:197], v[218:221], v[22:25]
	v_mfma_f32_16x16x32_bf16 v[10:13], v[186:189], v[226:229], v[10:13]
	v_mfma_f32_16x16x32_bf16 v[2:5], v[194:197], v[226:229], v[2:5]
	s_setprio 0
	s_barrier
	s_add_i32 s26, s26, 2
	s_add_u32 s10, s10, 0x100
	s_addc_u32 s11, s11, 0
	s_add_u32 s24, s24, 0x100
	s_addc_u32 s25, s25, 0
	s_cmp_gt_u32 s26, 13
	s_cbranch_scc1 .Lffnin_kdone

.Lffnin_kdone:
	s_and_b64 vcc, exec, s[4:5]
	s_cbranch_vccz .LBB0_129
	s_barrier

.LBB0_508:
	s_or_b64 exec, exec, s[48:49]
	v_lshl_add_u64 v[12:13], v[134:135], 0, s[44:45]
	v_lshl_add_u64 v[8:9], v[140:141], 1, v[12:13]
	global_load_dwordx4 v[66:69], v[8:9], off
	v_lshl_add_u64 v[8:9], v[142:143], 1, v[12:13]
	global_load_dwordx4 v[70:73], v[8:9], off
	v_lshl_add_u64 v[8:9], v[144:145], 1, v[12:13]
	global_load_dwordx4 v[74:77], v[8:9], off
	v_lshl_add_u64 v[8:9], v[146:147], 1, v[12:13]
	global_load_dwordx4 v[78:81], v[8:9], off
	s_add_i32 s24, s58, s13
	s_ashr_i32 s25, s24, 31
	s_lshl_b64 s[24:25], s[24:25], 18
	v_mov_b32_e32 v14, v1
	v_mov_b32_e32 v15, v1
	v_lshl_add_u64 v[130:131], v[6:7], 1, s[4:5]
	v_lshl_add_u64 v[132:133], v[4:5], 1, s[4:5]
	v_lshl_add_u64 v[152:153], v[2:3], 1, s[24:25]
	v_mov_b32_e32 v0, v1
	v_mov_b32_e32 v2, v1
	v_mov_b32_e32 v3, v1
	v_mov_b32_e32 v4, v1
	v_mov_b32_e32 v5, v1
	v_mov_b32_e32 v6, v1
	v_mov_b32_e32 v7, v1
	s_xor_b64 s[10:11], s[10:11], -1
	s_mov_b32 s23, 0
	v_mov_b32_e32 v154, 0
	s_mov_b32 s24, 2
	s_mov_b32 s25, s20
	s_mov_b32 s26, 0
	v_mov_b32_e32 v155, 0
	s_mov_b32 s27, 0
	s_waitcnt vmcnt(0)
	ds_write_b128 v215, v[66:69]
	ds_write_b128 v216, v[70:73]
	ds_write_b128 v217, v[74:77]
	ds_write_b128 v218, v[78:81]
	v_mov_b32_e32 v12, v1
	v_mov_b32_e32 v13, v1
	v_mov_b32_e32 v8, v1
	v_mov_b32_e32 v9, v1
	v_mov_b32_e32 v10, v1
	v_mov_b32_e32 v11, v1
	v_mov_b64_e32 v[64:65], v[14:15]
	v_mov_b64_e32 v[48:49], v[14:15]
	v_mov_b64_e32 v[32:33], v[14:15]
	v_mov_b64_e32 v[62:63], v[12:13]
	v_mov_b64_e32 v[60:61], v[10:11]
	v_mov_b64_e32 v[58:59], v[8:9]
	v_mov_b64_e32 v[56:57], v[6:7]
	v_mov_b64_e32 v[54:55], v[4:5]
	v_mov_b64_e32 v[52:53], v[2:3]
	v_mov_b64_e32 v[50:51], v[0:1]
	v_mov_b64_e32 v[46:47], v[12:13]
	v_mov_b64_e32 v[44:45], v[10:11]
	v_mov_b64_e32 v[42:43], v[8:9]
	v_mov_b64_e32 v[40:41], v[6:7]
	v_mov_b64_e32 v[38:39], v[4:5]
	v_mov_b64_e32 v[36:37], v[2:3]
	v_mov_b64_e32 v[34:35], v[0:1]
	v_mov_b64_e32 v[30:31], v[12:13]
	v_mov_b64_e32 v[28:29], v[10:11]
	v_mov_b64_e32 v[26:27], v[8:9]
	v_mov_b64_e32 v[24:25], v[6:7]
	v_mov_b64_e32 v[22:23], v[4:5]
	v_mov_b64_e32 v[20:21], v[2:3]
	v_mov_b64_e32 v[18:19], v[0:1]
	v_mov_b64_e32 v[16:17], v[14:15]
	v_mov_b64_e32 v[14:15], v[12:13]
	v_mov_b64_e32 v[12:13], v[10:11]
	v_mov_b64_e32 v[10:11], v[8:9]
	v_mov_b64_e32 v[8:9], v[6:7]
	v_mov_b64_e32 v[6:7], v[4:5]
	v_mov_b64_e32 v[4:5], v[2:3]
	v_mov_b64_e32 v[2:3], v[0:1]
	s_branch .LBB0_511

	.amdhsa_kernel _Z14fwd_megakernel4Args
		.amdhsa_group_segment_fixed_size 0
		.amdhsa_private_segment_fixed_size 0
		.amdhsa_kernarg_size 528
		.amdhsa_user_sgpr_count 2
		.amdhsa_user_sgpr_dispatch_ptr 0
		.amdhsa_user_sgpr_queue_ptr 0
		.amdhsa_user_sgpr_kernarg_segment_ptr 1
		.amdhsa_user_sgpr_dispatch_id 0
		.amdhsa_user_sgpr_kernarg_preload_length 0
		.amdhsa_user_sgpr_kernarg_preload_offset 0
		.amdhsa_user_sgpr_private_segment_size 0
		.amdhsa_uses_dynamic_stack 0
		.amdhsa_enable_private_segment 0
		.amdhsa_system_sgpr_workgroup_id_x 1
		.amdhsa_system_sgpr_workgroup_id_y 0
		.amdhsa_system_sgpr_workgroup_id_z 0
		.amdhsa_system_sgpr_workgroup_info 0
		.amdhsa_system_vgpr_workitem_id 2
		.amdhsa_next_free_vgpr 256
		.amdhsa_next_free_sgpr 102
		.amdhsa_accum_offset 256
		.amdhsa_reserve_vcc 1
		.amdhsa_float_round_mode_32 0
		.amdhsa_float_round_mode_16_64 0
		.amdhsa_float_denorm_mode_32 3
		.amdhsa_float_denorm_mode_16_64 3
		.amdhsa_dx10_clamp 1
		.amdhsa_ieee_mode 1
		.amdhsa_fp16_overflow 0
		.amdhsa_tg_split 0
		.amdhsa_exception_fp_ieee_invalid_op 0
		.amdhsa_exception_fp_denorm_src 0
		.amdhsa_exception_fp_ieee_div_zero 0
		.amdhsa_exception_fp_ieee_overflow 0
		.amdhsa_exception_fp_ieee_underflow 0
		.amdhsa_exception_fp_ieee_inexact 0
		.amdhsa_exception_int_div_zero 0
	.end_amdhsa_kernel

amdhsa.kernels:
  - .agpr_count:     0
    .args:
      - .offset:         0
        .size:           272
        .value_kind:     by_value
      - .offset:         272
        .size:           4
        .value_kind:     hidden_block_count_x
      - .offset:         276
        .size:           4
        .value_kind:     hidden_block_count_y
      - .offset:         280
        .size:           4
        .value_kind:     hidden_block_count_z
      - .offset:         284
        .size:           2
        .value_kind:     hidden_group_size_x
      - .offset:         286
        .size:           2
        .value_kind:     hidden_group_size_y
      - .offset:         288
        .size:           2
        .value_kind:     hidden_group_size_z
      - .offset:         290
        .size:           2
        .value_kind:     hidden_remainder_x
      - .offset:         292
        .size:           2
        .value_kind:     hidden_remainder_y
      - .offset:         294
        .size:           2
        .value_kind:     hidden_remainder_z
      - .offset:         312
        .size:           8
        .value_kind:     hidden_global_offset_x
      - .offset:         320
        .size:           8
        .value_kind:     hidden_global_offset_y
      - .offset:         328
        .size:           8
        .value_kind:     hidden_global_offset_z
      - .offset:         336
        .size:           2
        .value_kind:     hidden_grid_dims
      - .offset:         360
        .size:           8
        .value_kind:     hidden_multigrid_sync_arg
      - .offset:         392
        .size:           4
        .value_kind:     hidden_dynamic_lds_size
    .group_segment_fixed_size: 0
    .kernarg_segment_align: 8
    .kernarg_segment_size: 528
    .language:       OpenCL C
    .language_version:
      - 2
      - 0
    .max_flat_workgroup_size: 512
    .name:           _Z14fwd_megakernel4Args
    .private_segment_fixed_size: 0
    .sgpr_count:     108
    .sgpr_spill_count: 367
    .symbol:         _Z14fwd_megakernel4Args.kd
    .uniform_work_group_size: 1
    .uses_dynamic_stack: false
    .vgpr_count:     256
    .vgpr_spill_count: 0
    .wavefront_size: 64
